# strategy 8 on dilated attention: all 8 V^T fragment LDS reads of a tile issued right after its V ds_writes into phase-unused VGPRs, so the PV MFMAs run back to back behind the softmax VALU
# baseline (speedup 1.0000x reference)
; __device__ __forceinline__ void dil_unit(const bf16_t* QKV, float* scr, bf16_t* O, int b, int h, int blk, char* shm) {
;     ...
;             const int k = wid + 8 * rep, res = k & (d - 1), c = k >> lg, tq0 = T0 + res + d * 32 * c;
;             const int tq = tq0 + d * r32;
;             bf16x8 qf[4];
; #pragma unroll
;             for (int s = 0; s < 4; ++s) qf[s] = *(const bf16x8*)(Qh + (rb + tq) * 1536 + s * 16 + hi * 8);
;             f32x16 o[2]; o[0] = f32x16{}; o[1] = f32x16{};
;             float mrun = -1e30f, lrun = 0.f;
.LBB0_1247:
	s_add_i32 s0, s0, s28
	s_bfm_b32 s1, s30, 0
	s_and_b32 s1, s0, s1
	s_ashr_i32 s0, s0, s30
	s_add_i32 s8, s1, s93
	s_lshl_b32 s0, s0, s34
	s_add_i32 s8, s8, s0
	v_add_u32_e32 v174, s8, v180
	v_ashrrev_i32_e32 v175, 31, v174
	v_lshl_add_u64 v[172:173], v[174:175], 0, s[18:19]
	v_mad_u64_u32 v[0:1], s[0:1], v172, s81, v[160:161]
	v_mad_i32_i24 v1, v173, s81, v1
	s_mov_b32 s0, 4
	global_load_dwordx4 v[48:51], v[0:1], off
	global_load_dwordx4 v[52:55], v[0:1], off offset:32
	global_load_dwordx4 v[56:59], v[0:1], off offset:64
	global_load_dwordx4 v[60:63], v[0:1], off offset:96
	s_lshl_b32 s0, s0, 5
	s_add_i32 s3, s0, 0xffffff80
	v_or_b32_e32 v0, s3, v167
	v_lshlrev_b32_e32 v0, s30, v0
	v_add_u32_e32 v0, s8, v0
	v_max_i32_e32 v0, 0, v0
	v_add_u32_e32 v0, s18, v0
	v_mad_u64_u32 v[4:5], s[0:1], v0, s81, v[162:163]
	v_or_b32_e32 v28, s3, v176
	global_load_dwordx4 v[0:3], v[4:5], off
	global_load_dwordx4 v[24:27], v[4:5], off offset:32
	global_load_dwordx4 v[20:23], v[4:5], off offset:64
	global_load_dwordx4 v[16:19], v[4:5], off offset:96
	v_lshlrev_b32_e32 v4, s30, v28
	v_or_b32_e32 v8, 8, v28
	v_add_u32_e32 v4, s8, v4
	v_lshlrev_b32_e32 v8, s30, v8
	v_or_b32_e32 v12, 16, v28
	v_max_i32_e32 v4, 0, v4
	v_add_u32_e32 v8, s8, v8
	v_lshlrev_b32_e32 v12, s30, v12
	v_or_b32_e32 v28, 24, v28
	v_add_u32_e32 v4, s18, v4
	v_max_i32_e32 v8, 0, v8
	v_add_u32_e32 v12, s8, v12
	v_lshlrev_b32_e32 v28, s30, v28
	v_mad_u64_u32 v[4:5], s[0:1], v4, s81, v[164:165]
	v_add_u32_e32 v8, s18, v8
	v_max_i32_e32 v12, 0, v12
	v_add_u32_e32 v28, s8, v28
	global_load_dwordx4 v[4:7], v[4:5], off
	v_mad_u64_u32 v[8:9], s[0:1], v8, s81, v[164:165]
	v_add_u32_e32 v12, s18, v12
	v_max_i32_e32 v28, 0, v28
	global_load_dwordx4 v[8:11], v[8:9], off
	v_mad_u64_u32 v[12:13], s[0:1], v12, s81, v[164:165]
	v_add_u32_e32 v28, s18, v28
	global_load_dwordx4 v[12:15], v[12:13], off
	v_mad_u64_u32 v[28:29], s[0:1], v28, s81, v[164:165]
	global_load_dwordx4 v[28:31], v[28:29], off
	s_mov_b32 s0, 3
	s_lshl_b32 s0, s0, 5
	s_add_i32 s3, s0, 0xffffff80
	v_or_b32_e32 v32, s3, v167
	v_lshlrev_b32_e32 v32, s30, v32
	v_add_u32_e32 v32, s8, v32
	v_max_i32_e32 v32, 0, v32
	v_add_u32_e32 v32, s18, v32
	v_mad_u64_u32 v[36:37], s[0:1], v32, s81, v[162:163]
	s_waitcnt vmcnt(16)
	v_or_b32_e32 v64, s3, v176
	global_load_dwordx4 v[32:35], v[36:37], off
	global_load_dwordx4 v[132:135], v[36:37], off offset:32
	global_load_dwordx4 v[128:131], v[36:37], off offset:64
	global_load_dwordx4 v[124:127], v[36:37], off offset:96
	v_lshlrev_b32_e32 v36, s30, v64
	v_or_b32_e32 v40, 8, v64
	v_or_b32_e32 v44, 16, v64
	v_or_b32_e32 v64, 24, v64
	v_lshlrev_b32_e32 v40, s30, v40
	v_lshlrev_b32_e32 v44, s30, v44
	v_lshlrev_b32_e32 v64, s30, v64
	v_add_u32_e32 v36, s8, v36
	v_add_u32_e32 v40, s8, v40
	v_add_u32_e32 v44, s8, v44
	v_add_u32_e32 v64, s8, v64
	v_max_i32_e32 v36, 0, v36
	v_max_i32_e32 v40, 0, v40
	v_max_i32_e32 v44, 0, v44
	v_max_i32_e32 v64, 0, v64
	v_add_u32_e32 v36, s18, v36
	v_add_u32_e32 v40, s18, v40
	v_add_u32_e32 v44, s18, v44
	v_add_u32_e32 v64, s18, v64
	v_mad_u64_u32 v[36:37], s[0:1], v36, s81, v[164:165]
	v_mad_u64_u32 v[40:41], s[0:1], v40, s81, v[164:165]
	v_mad_u64_u32 v[44:45], s[0:1], v44, s81, v[164:165]
	v_mad_u64_u32 v[64:65], s[0:1], v64, s81, v[164:165]
	s_mov_b32 s0, 2
	global_load_dwordx4 v[36:39], v[36:37], off
	s_nop 0
	global_load_dwordx4 v[40:43], v[40:41], off
	s_nop 0
	global_load_dwordx4 v[44:47], v[44:45], off
	s_nop 0
	global_load_dwordx4 v[136:139], v[64:65], off
	s_lshl_b32 s0, s0, 5
	s_add_i32 s3, s0, 0xffffff80
	v_or_b32_e32 v64, s3, v167
	v_or_b32_e32 v78, s3, v176
	v_lshlrev_b32_e32 v64, s30, v64
	v_lshlrev_b32_e32 v76, s30, v78
	v_add_u32_e32 v64, s8, v64
	v_add_u32_e32 v76, s8, v76
	v_max_i32_e32 v64, 0, v64
	v_max_i32_e32 v76, 0, v76
	v_add_u32_e32 v64, s18, v64
	v_add_u32_e32 v76, s18, v76
	v_mad_u64_u32 v[64:65], s[0:1], v64, s81, v[162:163]
	v_mad_u64_u32 v[76:77], s[0:1], v76, s81, v[164:165]
	global_load_dwordx4 v[92:95], v[64:65], off
	global_load_dwordx4 v[72:75], v[64:65], off offset:32
	global_load_dwordx4 v[68:71], v[64:65], off offset:64
	s_nop 0
	global_load_dwordx4 v[64:67], v[64:65], off offset:96
	s_not_b32 s3, s8
	global_load_dwordx4 v[112:115], v[76:77], off
	v_or_b32_e32 v76, 8, v78
	v_lshlrev_b32_e32 v76, s30, v76
	v_add_u32_e32 v76, s8, v76
	v_max_i32_e32 v76, 0, v76
	v_add_u32_e32 v76, s18, v76
	v_mad_u64_u32 v[76:77], s[0:1], v76, s81, v[164:165]
	global_load_dwordx4 v[116:119], v[76:77], off
	v_or_b32_e32 v76, 16, v78
	v_lshlrev_b32_e32 v76, s30, v76
	v_add_u32_e32 v76, s8, v76
	v_max_i32_e32 v76, 0, v76
	v_add_u32_e32 v76, s18, v76
	v_mad_u64_u32 v[76:77], s[0:1], v76, s81, v[164:165]
	global_load_dwordx4 v[120:123], v[76:77], off
	v_or_b32_e32 v76, 24, v78
	v_lshlrev_b32_e32 v76, s30, v76
	v_add_u32_e32 v76, s8, v76
	v_max_i32_e32 v76, 0, v76
	v_add_u32_e32 v76, s18, v76
	v_mad_u64_u32 v[76:77], s[0:1], v76, s81, v[164:165]
	s_mov_b32 s0, 4
	global_load_dwordx4 v[140:143], v[76:77], off
	s_waitcnt lgkmcnt(0)
	s_waitcnt vmcnt(19)
	ds_write_b128 v178, v[4:7]
	s_waitcnt vmcnt(18)
	ds_write_b128 v178, v[8:11] offset:512
	s_waitcnt vmcnt(17)
	ds_write_b128 v178, v[12:15] offset:1024
	s_waitcnt vmcnt(16)
	ds_write_b128 v178, v[28:31] offset:1536
	ds_read_b64_tr_b16 v[184:185], v179
	ds_read_b64_tr_b16 v[186:187], v179 offset:512
	ds_read_b64_tr_b16 v[188:189], v179 offset:1024
	ds_read_b64_tr_b16 v[190:191], v179 offset:1536
	ds_read_b64_tr_b16 v[192:193], v179 offset:2048
	ds_read_b64_tr_b16 v[194:195], v179 offset:2560
	ds_read_b64_tr_b16 v[196:197], v179 offset:3072
	ds_read_b64_tr_b16 v[198:199], v179 offset:3584
	v_mfma_f32_32x32x16_bf16 v[0:15], v[0:3], v[48:51], 0
	v_mfma_f32_32x32x16_bf16 v[0:15], v[24:27], v[52:55], v[0:15]
	v_mfma_f32_32x32x16_bf16 v[0:15], v[20:23], v[56:59], v[0:15]
	v_mfma_f32_32x32x16_bf16 v[0:15], v[16:19], v[60:63], v[0:15]
	v_lshl_add_u32 v16, s0, 5, v177
	v_sub_u32_e32 v211, v167, v16
	v_cmp_lt_i32_e32 vcc, 0x80, v211
	v_lshlrev_b32_e32 v170, s30, v16
	s_nop 2
	s_cbranch_vccnz .Ldil_slow_0
	v_cmp_ge_i32_e32 vcc, s3, v170
	s_nop 3
	s_cbranch_vccnz .Ldil_slow_0
	v_cvt_f32_i32_e32 v170, v211
	v_mul_f32_e32 v170, v171, v170
	v_fma_f32 v0, v0, v210, -v170
	v_cmp_le_i32_e32 vcc, 0, v211
	v_fma_f32 v1, v1, v210, -v170
	v_fmamk_f32 v1, v171, 0x3f800000, v1
	v_cndmask_b32_e32 v0, v243, v0, vcc
	v_cmp_le_i32_e32 vcc, 1, v211
	v_fma_f32 v17, v2, v210, -v170
	v_fmamk_f32 v17, v171, 0x40000000, v17
	v_cndmask_b32_e32 v1, v243, v1, vcc
	v_cmp_le_i32_e32 vcc, 2, v211
	v_fma_f32 v19, v3, v210, -v170
	v_fmamk_f32 v19, v171, 0x40400000, v19
	v_cndmask_b32_e32 v17, v243, v17, vcc
	v_cmp_le_i32_e32 vcc, 3, v211
	v_fma_f32 v4, v4, v210, -v170
	v_fmamk_f32 v4, v171, 0x41000000, v4
	v_cndmask_b32_e32 v19, v243, v19, vcc
	v_cmp_le_i32_e32 vcc, 8, v211
	v_fma_f32 v5, v5, v210, -v170
	v_fmamk_f32 v5, v171, 0x41100000, v5
	v_cndmask_b32_e32 v4, v243, v4, vcc
	v_cmp_le_i32_e32 vcc, 9, v211
	v_fma_f32 v6, v6, v210, -v170
	v_fmamk_f32 v6, v171, 0x41200000, v6
	v_cndmask_b32_e32 v5, v243, v5, vcc
	v_cmp_le_i32_e32 vcc, 10, v211
	v_fma_f32 v7, v7, v210, -v170
	v_fmamk_f32 v7, v171, 0x41300000, v7
	v_cndmask_b32_e32 v6, v243, v6, vcc
	v_cmp_le_i32_e32 vcc, 11, v211
	v_fma_f32 v8, v8, v210, -v170
	v_fmamk_f32 v8, v171, 0x41800000, v8
	v_cndmask_b32_e32 v7, v243, v7, vcc
	v_cmp_le_i32_e32 vcc, 16, v211
	v_fma_f32 v9, v9, v210, -v170
	v_fmamk_f32 v9, v171, 0x41880000, v9
	v_cndmask_b32_e32 v8, v243, v8, vcc
	v_cmp_le_i32_e32 vcc, 17, v211
	v_fma_f32 v10, v10, v210, -v170
	v_fmamk_f32 v10, v171, 0x41900000, v10
	v_cndmask_b32_e32 v9, v243, v9, vcc
	v_cmp_le_i32_e32 vcc, 18, v211
	v_fma_f32 v11, v11, v210, -v170
	v_fmamk_f32 v11, v171, 0x41980000, v11
	v_cndmask_b32_e32 v10, v243, v10, vcc
	v_cmp_le_i32_e32 vcc, 19, v211
	v_fma_f32 v12, v12, v210, -v170
	v_fmamk_f32 v12, v171, 0x41c00000, v12
	v_cndmask_b32_e32 v11, v243, v11, vcc
	v_cmp_le_i32_e32 vcc, 24, v211
	v_fma_f32 v13, v13, v210, -v170
	v_fmamk_f32 v13, v171, 0x41c80000, v13
	v_cndmask_b32_e32 v12, v243, v12, vcc
	v_cmp_le_i32_e32 vcc, 25, v211
	v_fma_f32 v14, v14, v210, -v170
	v_fmamk_f32 v14, v171, 0x41d00000, v14
	v_cndmask_b32_e32 v13, v243, v13, vcc
	v_cmp_le_i32_e32 vcc, 26, v211
	v_fma_f32 v2, v15, v210, -v170
	v_fmamk_f32 v2, v171, 0x41d80000, v2
	v_cndmask_b32_e32 v14, v243, v14, vcc
	v_cmp_le_i32_e32 vcc, 27, v211
	s_nop 1
	v_cndmask_b32_e32 v2, v243, v2, vcc
	s_branch .Ldil_join_0

.Ldil_join_0:
	v_max_f32_e32 v20, v14, v2
	v_max_f32_e32 v3, v17, v19
	v_max_f32_e32 v15, v6, v7
	v_max_f32_e32 v16, v8, v9
	v_max_f32_e32 v18, v10, v11
	v_max3_f32 v20, v12, v13, v20
	v_max3_f32 v3, v0, v1, v3
	v_max3_f32 v15, v4, v5, v15
	v_max3_f32 v16, v16, v18, v20
	v_max3_f32 v3, v3, v15, v16
	v_mov_b32_e32 v15, v3
	s_nop 1
	v_permlane32_swap_b32_e32 v3, v15
	s_mov_b32 s0, 0xf149f2ca
	v_max3_f32 v144, v3, v15, s0
	v_sub_f32_e32 v0, v0, v144
	v_exp_f32_e32 v16, v0
	v_sub_f32_e32 v0, v1, v144
	v_exp_f32_e32 v18, v0
	v_sub_f32_e32 v0, v17, v144
	v_exp_f32_e32 v20, v0
	v_sub_f32_e32 v0, v19, v144
	v_exp_f32_e32 v22, v0
	v_sub_f32_e32 v0, v4, v144
	v_exp_f32_e32 v24, v0
	v_sub_f32_e32 v0, v5, v144
	v_exp_f32_e32 v26, v0
	v_sub_f32_e32 v0, v6, v144
	v_exp_f32_e32 v28, v0
	v_sub_f32_e32 v0, v7, v144
	v_exp_f32_e32 v30, v0
	v_sub_f32_e32 v0, v8, v144
	v_exp_f32_e32 v17, v0
	v_sub_f32_e32 v0, v9, v144
	v_exp_f32_e32 v19, v0
	v_sub_f32_e32 v0, v10, v144
	v_exp_f32_e32 v21, v0
	v_sub_f32_e32 v0, v11, v144
	v_exp_f32_e32 v23, v0
	v_sub_f32_e32 v0, v12, v144
	v_exp_f32_e32 v25, v0
	v_sub_f32_e32 v0, v13, v144
	v_exp_f32_e32 v27, v0
	v_sub_f32_e32 v0, v14, v144
	v_exp_f32_e32 v29, v0
	v_sub_f32_e32 v0, v2, v144
	v_exp_f32_e32 v31, v0
	v_sub_f32_e32 v3, 0xf149f2ca, v144
	v_exp_f32_e32 v76, v3
	v_pk_add_f32 v[0:1], v[16:17], v[18:19]
	v_pk_add_f32 v[2:3], v[20:21], v[22:23]
	v_pk_add_f32 v[4:5], v[28:29], v[30:31]
	v_pk_add_f32 v[0:1], v[0:1], v[2:3]
	v_pk_add_f32 v[2:3], v[24:25], v[26:27]
	s_cmp_lt_i32 s8, s31
	v_pk_add_f32 v[2:3], v[2:3], v[4:5]
	s_nop 0
	v_pk_add_f32 v[0:1], v[0:1], v[2:3]
	s_nop 0
	v_add_f32_e32 v145, v0, v1
	v_mul_f32_e32 v0, 0, v76
	v_fmac_f32_e32 v145, 0, v76
	v_cvt_pk_bf16_f32 v76, v16, v18
	v_cvt_pk_bf16_f32 v77, v20, v22
	v_cvt_pk_bf16_f32 v78, v24, v26
	v_cvt_pk_bf16_f32 v79, v28, v30
	v_cvt_pk_bf16_f32 v80, v17, v19
	v_cvt_pk_bf16_f32 v81, v21, v23
	v_cvt_pk_bf16_f32 v82, v25, v27
	v_cvt_pk_bf16_f32 v83, v29, v31
	s_waitcnt lgkmcnt(0)
	v_mov_b32_e32 v1, v0
	v_mov_b32_e32 v2, v0
	v_mov_b32_e32 v3, v0
	v_mov_b32_e32 v4, v0
	v_mov_b32_e32 v5, v0
	v_mov_b32_e32 v6, v0
	v_mov_b32_e32 v7, v0
	v_mov_b32_e32 v8, v0
	v_mov_b32_e32 v9, v0
	v_mov_b32_e32 v10, v0
	v_mov_b32_e32 v11, v0
	v_mov_b32_e32 v12, v0
	v_mov_b32_e32 v13, v0
	v_mov_b32_e32 v14, v0
	v_mov_b32_e32 v15, v0
	s_nop 0
	s_nop 1
	v_mfma_f32_32x32x16_bf16 v[16:31], v[184:187], v[76:79], v[0:15]
	v_mfma_f32_32x32x16_bf16 v[16:31], v[188:191], v[80:83], v[16:31]
	v_mfma_f32_32x32x16_bf16 v[0:15], v[192:195], v[76:79], v[0:15]
	v_mfma_f32_32x32x16_bf16 v[0:15], v[196:199], v[80:83], v[0:15]
	s_cbranch_scc1 .LBB0_1255
	s_mov_b32 s0, 1
	s_lshl_b32 s0, s0, 5
	s_add_i32 s9, s0, 0xffffff80
	v_or_b32_e32 v108, s9, v176
	v_or_b32_e32 v76, s9, v167
	v_lshlrev_b32_e32 v96, s30, v108
	v_or_b32_e32 v100, 8, v108
	v_or_b32_e32 v104, 16, v108
	v_or_b32_e32 v108, 24, v108
	v_lshlrev_b32_e32 v76, s30, v76
	v_lshlrev_b32_e32 v100, s30, v100
	v_lshlrev_b32_e32 v104, s30, v104
	v_lshlrev_b32_e32 v108, s30, v108
	v_add_u32_e32 v76, s8, v76
	v_add_u32_e32 v96, s8, v96
	v_add_u32_e32 v100, s8, v100
	v_add_u32_e32 v104, s8, v104
	v_add_u32_e32 v108, s8, v108
	v_max_i32_e32 v76, 0, v76
	v_max_i32_e32 v96, 0, v96
	v_max_i32_e32 v100, 0, v100
	v_max_i32_e32 v104, 0, v104
	v_max_i32_e32 v108, 0, v108
	v_add_u32_e32 v76, s18, v76
	v_add_u32_e32 v96, s18, v96
	v_add_u32_e32 v100, s18, v100
	v_add_u32_e32 v104, s18, v104
	v_add_u32_e32 v108, s18, v108
	v_mad_u64_u32 v[88:89], s[0:1], v76, s81, v[162:163]
	v_mad_u64_u32 v[96:97], s[0:1], v96, s81, v[164:165]
	v_mad_u64_u32 v[100:101], s[0:1], v100, s81, v[164:165]
	v_mad_u64_u32 v[104:105], s[0:1], v104, s81, v[164:165]
	v_mad_u64_u32 v[108:109], s[0:1], v108, s81, v[164:165]
	s_mov_b32 s0, 3
	global_load_dwordx4 v[76:79], v[88:89], off
	global_load_dwordx4 v[80:83], v[88:89], off offset:32
	global_load_dwordx4 v[84:87], v[88:89], off offset:64
	s_nop 0
	global_load_dwordx4 v[88:91], v[88:89], off offset:96
	s_nop 0
	global_load_dwordx4 v[96:99], v[96:97], off
	s_nop 0
	global_load_dwordx4 v[100:103], v[100:101], off
	s_nop 0
	global_load_dwordx4 v[104:107], v[104:105], off
	s_nop 0
	global_load_dwordx4 v[108:111], v[108:109], off
	s_waitcnt lgkmcnt(0)
	s_waitcnt vmcnt(19)
	ds_write_b128 v178, v[36:39]
	s_waitcnt vmcnt(18)
	ds_write_b128 v178, v[40:43] offset:512
	s_waitcnt vmcnt(17)
	ds_write_b128 v178, v[44:47] offset:1024
	s_waitcnt vmcnt(16)
	ds_write_b128 v178, v[136:139] offset:1536
	ds_read_b64_tr_b16 v[184:185], v179
	ds_read_b64_tr_b16 v[186:187], v179 offset:512
	ds_read_b64_tr_b16 v[188:189], v179 offset:1024
	ds_read_b64_tr_b16 v[190:191], v179 offset:1536
	ds_read_b64_tr_b16 v[192:193], v179 offset:2048
	ds_read_b64_tr_b16 v[194:195], v179 offset:2560
	ds_read_b64_tr_b16 v[196:197], v179 offset:3072
	ds_read_b64_tr_b16 v[198:199], v179 offset:3584
	v_mfma_f32_32x32x16_bf16 v[32:47], v[32:35], v[48:51], 0
	v_mfma_f32_32x32x16_bf16 v[32:47], v[132:135], v[52:55], v[32:47]
	v_mfma_f32_32x32x16_bf16 v[32:47], v[128:131], v[56:59], v[32:47]
	v_mfma_f32_32x32x16_bf16 v[32:47], v[124:127], v[60:63], v[32:47]
	v_lshl_add_u32 v124, s0, 5, v177
	v_sub_u32_e32 v211, v167, v124
	v_add_u32_e32 v170, 0xffffffe5, v211
	v_cmp_le_u32_e32 vcc, 0x66, v170
	v_lshlrev_b32_e32 v170, s30, v124
	s_nop 2
	s_cbranch_vccnz .Ldil_slow_1
	v_cmp_ge_i32_e32 vcc, s3, v170
	s_nop 3
	s_cbranch_vccnz .Ldil_slow_1
	v_cvt_f32_i32_e32 v170, v211
	v_mul_f32_e32 v170, v171, v170
	v_fma_f32 v32, v32, v210, -v170
	v_fma_f32 v33, v33, v210, -v170
	v_fmamk_f32 v33, v171, 0x3f800000, v33
	v_fma_f32 v125, v34, v210, -v170
	v_fmamk_f32 v125, v171, 0x40000000, v125
	v_fma_f32 v126, v35, v210, -v170
	v_fmamk_f32 v126, v171, 0x40400000, v126
	v_fma_f32 v127, v36, v210, -v170
	v_fmamk_f32 v127, v171, 0x41000000, v127
	v_fma_f32 v37, v37, v210, -v170
	v_fmamk_f32 v37, v171, 0x41100000, v37
	v_fma_f32 v128, v38, v210, -v170
	v_fmamk_f32 v128, v171, 0x41200000, v128
	v_fma_f32 v39, v39, v210, -v170
	v_fmamk_f32 v39, v171, 0x41300000, v39
	v_fma_f32 v129, v40, v210, -v170
	v_fmamk_f32 v129, v171, 0x41800000, v129
	v_fma_f32 v41, v41, v210, -v170
	v_fmamk_f32 v41, v171, 0x41880000, v41
	v_fma_f32 v130, v42, v210, -v170
	v_fmamk_f32 v130, v171, 0x41900000, v130
	v_fma_f32 v43, v43, v210, -v170
	v_fmamk_f32 v43, v171, 0x41980000, v43
	v_fma_f32 v131, v44, v210, -v170
	v_fmamk_f32 v131, v171, 0x41c00000, v131
	v_fma_f32 v132, v45, v210, -v170
	v_fmamk_f32 v132, v171, 0x41c80000, v132
	v_fma_f32 v133, v46, v210, -v170
	v_fmamk_f32 v133, v171, 0x41d00000, v133
	v_fma_f32 v34, v47, v210, -v170
	v_fmamk_f32 v34, v171, 0x41d80000, v34
	s_branch .Ldil_join_1

.Ldil_join_1:
	v_max_f32_e32 v42, v133, v34
	v_max_f32_e32 v35, v125, v126
	v_max_f32_e32 v36, v128, v39
	v_max_f32_e32 v38, v129, v41
	v_max_f32_e32 v40, v130, v43
	v_max3_f32 v42, v131, v132, v42
	v_max3_f32 v35, v32, v33, v35
	v_max3_f32 v36, v127, v37, v36
	v_max3_f32 v38, v38, v40, v42
	v_max3_f32 v35, v35, v36, v38
	v_mov_b32_e32 v36, v35
	s_nop 1
	v_permlane32_swap_b32_e32 v35, v36
	v_max3_f32 v181, v144, v35, v36
	v_sub_f32_e32 v32, v32, v181
	v_exp_f32_e32 v36, v32
	v_sub_f32_e32 v32, v33, v181
	v_exp_f32_e32 v38, v32
	v_sub_f32_e32 v32, v125, v181
	v_exp_f32_e32 v40, v32
	v_sub_f32_e32 v32, v126, v181
	v_exp_f32_e32 v42, v32
	v_sub_f32_e32 v32, v127, v181
	v_exp_f32_e32 v44, v32
	v_sub_f32_e32 v32, v37, v181
	v_exp_f32_e32 v46, v32
	v_sub_f32_e32 v32, v128, v181
	v_exp_f32_e32 v124, v32
	v_sub_f32_e32 v32, v39, v181
	v_exp_f32_e32 v126, v32
	v_sub_f32_e32 v32, v129, v181
	v_exp_f32_e32 v37, v32
	v_sub_f32_e32 v32, v41, v181
	v_exp_f32_e32 v39, v32
	v_sub_f32_e32 v32, v130, v181
	v_exp_f32_e32 v41, v32
	v_sub_f32_e32 v32, v43, v181
	v_exp_f32_e32 v43, v32
	v_sub_f32_e32 v32, v131, v181
	v_exp_f32_e32 v45, v32
	v_sub_f32_e32 v32, v132, v181
	v_exp_f32_e32 v47, v32
	v_sub_f32_e32 v32, v133, v181
	v_exp_f32_e32 v125, v32
	v_sub_f32_e32 v32, v34, v181
	v_exp_f32_e32 v127, v32
	v_sub_f32_e32 v35, v144, v181
	v_exp_f32_e32 v32, v35
	v_pk_add_f32 v[34:35], v[36:37], v[38:39]
	v_pk_add_f32 v[128:129], v[40:41], v[42:43]
	v_pk_add_f32 v[130:131], v[124:125], v[126:127]
	v_pk_add_f32 v[34:35], v[34:35], v[128:129]
	v_pk_add_f32 v[128:129], v[44:45], v[46:47]
	v_pk_mul_f32 v[30:31], v[30:31], v[32:33] op_sel_hi:[1,0]
	v_pk_add_f32 v[128:129], v[128:129], v[130:131]
	v_pk_mul_f32 v[28:29], v[28:29], v[32:33] op_sel_hi:[1,0]
	v_pk_add_f32 v[34:35], v[34:35], v[128:129]
	v_pk_mul_f32 v[26:27], v[26:27], v[32:33] op_sel_hi:[1,0]
	v_add_f32_e32 v175, v34, v35
	v_pk_mul_f32 v[24:25], v[24:25], v[32:33] op_sel_hi:[1,0]
	v_pk_mul_f32 v[22:23], v[22:23], v[32:33] op_sel_hi:[1,0]
	v_pk_mul_f32 v[20:21], v[20:21], v[32:33] op_sel_hi:[1,0]
	v_pk_mul_f32 v[18:19], v[18:19], v[32:33] op_sel_hi:[1,0]
	v_pk_mul_f32 v[16:17], v[16:17], v[32:33] op_sel_hi:[1,0]
	v_pk_mul_f32 v[14:15], v[14:15], v[32:33] op_sel_hi:[1,0]
	v_pk_mul_f32 v[12:13], v[12:13], v[32:33] op_sel_hi:[1,0]
	v_pk_mul_f32 v[10:11], v[10:11], v[32:33] op_sel_hi:[1,0]
	v_pk_mul_f32 v[8:9], v[8:9], v[32:33] op_sel_hi:[1,0]
	v_pk_mul_f32 v[6:7], v[6:7], v[32:33] op_sel_hi:[1,0]
	v_pk_mul_f32 v[4:5], v[4:5], v[32:33] op_sel_hi:[1,0]
	v_pk_mul_f32 v[2:3], v[2:3], v[32:33] op_sel_hi:[1,0]
	v_pk_mul_f32 v[0:1], v[0:1], v[32:33] op_sel_hi:[1,0]
	v_fmac_f32_e32 v175, v145, v32
	v_cvt_pk_bf16_f32 v32, v36, v38
	v_cvt_pk_bf16_f32 v33, v40, v42
	v_cvt_pk_bf16_f32 v34, v44, v46
	v_cvt_pk_bf16_f32 v35, v124, v126
	v_cvt_pk_bf16_f32 v36, v37, v39
	v_cvt_pk_bf16_f32 v37, v41, v43
	v_cvt_pk_bf16_f32 v38, v45, v47
	v_cvt_pk_bf16_f32 v39, v125, v127
	s_waitcnt lgkmcnt(0)
	s_cmp_lt_i32 s8, s35
	s_nop 1
	v_mfma_f32_32x32x16_bf16 v[16:31], v[184:187], v[32:35], v[16:31]
	v_mfma_f32_32x32x16_bf16 v[16:31], v[188:191], v[36:39], v[16:31]
	v_mfma_f32_32x32x16_bf16 v[0:15], v[192:195], v[32:35], v[0:15]
	v_mfma_f32_32x32x16_bf16 v[0:15], v[196:199], v[36:39], v[0:15]
	s_cbranch_scc1 .LBB0_1254
	s_mov_b32 s0, s19
	s_lshl_b32 s0, s0, 5
	s_add_i32 s9, s0, 0xffffff80
	v_or_b32_e32 v32, s9, v167
	v_lshlrev_b32_e32 v32, s30, v32
	v_add_u32_e32 v32, s8, v32
	v_max_i32_e32 v32, 0, v32
	v_add_u32_e32 v32, s18, v32
	v_mad_u64_u32 v[32:33], s[0:1], v32, s81, v[162:163]
	v_or_b32_e32 v34, s9, v176
	global_load_dwordx4 v[124:127], v[32:33], off
	global_load_dwordx4 v[128:131], v[32:33], off offset:32
	global_load_dwordx4 v[132:135], v[32:33], off offset:64
	global_load_dwordx4 v[136:139], v[32:33], off offset:96
	v_lshlrev_b32_e32 v32, s30, v34
	v_add_u32_e32 v32, s8, v32
	v_max_i32_e32 v32, 0, v32
	v_add_u32_e32 v32, s18, v32
	v_mad_u64_u32 v[32:33], s[0:1], v32, s81, v[164:165]
	global_load_dwordx4 v[144:147], v[32:33], off
	v_or_b32_e32 v32, 8, v34
	v_lshlrev_b32_e32 v32, s30, v32
	v_add_u32_e32 v32, s8, v32
	v_max_i32_e32 v32, 0, v32
	v_add_u32_e32 v32, s18, v32
	v_mad_u64_u32 v[32:33], s[0:1], v32, s81, v[164:165]
	global_load_dwordx4 v[148:151], v[32:33], off
	v_or_b32_e32 v32, 16, v34
	v_lshlrev_b32_e32 v32, s30, v32
	v_add_u32_e32 v32, s8, v32
	v_max_i32_e32 v32, 0, v32
	v_add_u32_e32 v32, s18, v32
	v_mad_u64_u32 v[32:33], s[0:1], v32, s81, v[164:165]
	global_load_dwordx4 v[152:155], v[32:33], off
	v_or_b32_e32 v32, 24, v34
	v_lshlrev_b32_e32 v32, s30, v32
	v_add_u32_e32 v32, s8, v32
	v_max_i32_e32 v32, 0, v32
	v_add_u32_e32 v32, s18, v32
	v_mad_u64_u32 v[32:33], s[0:1], v32, s81, v[164:165]
	global_load_dwordx4 v[156:159], v[32:33], off
	s_waitcnt vmcnt(23)
	v_mfma_f32_32x32x16_bf16 v[32:47], v[92:95], v[48:51], 0
	s_mov_b32 s0, 2
	s_waitcnt lgkmcnt(0)
	s_waitcnt vmcnt(19)
	ds_write_b128 v178, v[112:115]
	s_waitcnt vmcnt(18)
	ds_write_b128 v178, v[116:119] offset:512
	s_waitcnt vmcnt(17)
	ds_write_b128 v178, v[120:123] offset:1024
	s_waitcnt vmcnt(16)
	ds_write_b128 v178, v[140:143] offset:1536
	ds_read_b64_tr_b16 v[184:185], v179
	ds_read_b64_tr_b16 v[186:187], v179 offset:512
	ds_read_b64_tr_b16 v[188:189], v179 offset:1024
	ds_read_b64_tr_b16 v[190:191], v179 offset:1536
	ds_read_b64_tr_b16 v[192:193], v179 offset:2048
	ds_read_b64_tr_b16 v[194:195], v179 offset:2560
	ds_read_b64_tr_b16 v[196:197], v179 offset:3072
	ds_read_b64_tr_b16 v[198:199], v179 offset:3584
	v_mfma_f32_32x32x16_bf16 v[32:47], v[72:75], v[52:55], v[32:47]
	v_mfma_f32_32x32x16_bf16 v[32:47], v[68:71], v[56:59], v[32:47]
	v_mfma_f32_32x32x16_bf16 v[32:47], v[64:67], v[60:63], v[32:47]
	v_lshl_add_u32 v64, s0, 5, v177
	v_sub_u32_e32 v211, v167, v64
	v_add_u32_e32 v170, 0xffffffe5, v211
	v_cmp_le_u32_e32 vcc, 0x66, v170
	v_lshlrev_b32_e32 v170, s30, v64
	s_nop 2
	s_cbranch_vccnz .Ldil_slow_2
	v_cmp_ge_i32_e32 vcc, s3, v170
	s_nop 3
	s_cbranch_vccnz .Ldil_slow_2
	v_cvt_f32_i32_e32 v170, v211
	v_mul_f32_e32 v170, v171, v170
	v_fma_f32 v32, v32, v210, -v170
	v_fma_f32 v33, v33, v210, -v170
	v_fmamk_f32 v33, v171, 0x3f800000, v33
	v_fma_f32 v65, v34, v210, -v170
	v_fmamk_f32 v65, v171, 0x40000000, v65
	v_fma_f32 v66, v35, v210, -v170
	v_fmamk_f32 v66, v171, 0x40400000, v66
	v_fma_f32 v68, v36, v210, -v170
	v_fmamk_f32 v68, v171, 0x41000000, v68
	v_fma_f32 v37, v37, v210, -v170
	v_fmamk_f32 v37, v171, 0x41100000, v37
	v_fma_f32 v69, v38, v210, -v170
	v_fmamk_f32 v69, v171, 0x41200000, v69
	v_fma_f32 v39, v39, v210, -v170
	v_fmamk_f32 v39, v171, 0x41300000, v39
	v_fma_f32 v71, v40, v210, -v170
	v_fmamk_f32 v71, v171, 0x41800000, v71
	v_fma_f32 v41, v41, v210, -v170
	v_fmamk_f32 v41, v171, 0x41880000, v41
	v_fma_f32 v72, v42, v210, -v170
	v_fmamk_f32 v72, v171, 0x41900000, v72
	v_fma_f32 v43, v43, v210, -v170
	v_fmamk_f32 v43, v171, 0x41980000, v43
	v_fma_f32 v73, v44, v210, -v170
	v_fmamk_f32 v73, v171, 0x41c00000, v73
	v_fma_f32 v74, v45, v210, -v170
	v_fmamk_f32 v74, v171, 0x41c80000, v74
	v_fma_f32 v75, v46, v210, -v170
	v_fmamk_f32 v75, v171, 0x41d00000, v75
	v_fma_f32 v34, v47, v210, -v170
	v_fmamk_f32 v34, v171, 0x41d80000, v34
	s_branch .Ldil_join_2

.Ldil_join_2:
	v_max_f32_e32 v42, v75, v34
	v_max_f32_e32 v35, v65, v66
	v_max_f32_e32 v36, v69, v39
	v_max_f32_e32 v38, v71, v41
	v_max_f32_e32 v40, v72, v43
	v_max3_f32 v42, v73, v74, v42
	v_max3_f32 v35, v32, v33, v35
	v_max3_f32 v36, v68, v37, v36
	v_max3_f32 v38, v38, v40, v42
	v_max3_f32 v35, v35, v36, v38
	v_mov_b32_e32 v36, v35
	s_nop 1
	v_permlane32_swap_b32_e32 v35, v36
	v_max3_f32 v67, v181, v35, v36
	v_sub_f32_e32 v32, v32, v67
	v_exp_f32_e32 v36, v32
	v_sub_f32_e32 v32, v33, v67
	v_exp_f32_e32 v38, v32
	v_sub_f32_e32 v32, v65, v67
	v_exp_f32_e32 v40, v32
	v_sub_f32_e32 v32, v66, v67
	v_exp_f32_e32 v42, v32
	v_sub_f32_e32 v32, v68, v67
	v_exp_f32_e32 v44, v32
	v_sub_f32_e32 v32, v37, v67
	v_exp_f32_e32 v46, v32
	v_sub_f32_e32 v32, v69, v67
	v_exp_f32_e32 v68, v32
	v_sub_f32_e32 v32, v39, v67
	v_exp_f32_e32 v70, v32
	v_sub_f32_e32 v32, v71, v67
	v_exp_f32_e32 v37, v32
	v_sub_f32_e32 v32, v41, v67
	v_exp_f32_e32 v39, v32
	v_sub_f32_e32 v32, v72, v67
	v_exp_f32_e32 v41, v32
	v_sub_f32_e32 v32, v43, v67
	v_exp_f32_e32 v43, v32
	v_sub_f32_e32 v32, v73, v67
	v_exp_f32_e32 v45, v32
	v_sub_f32_e32 v32, v74, v67
	v_exp_f32_e32 v47, v32
	v_sub_f32_e32 v32, v75, v67
	v_exp_f32_e32 v69, v32
	v_sub_f32_e32 v32, v34, v67
	v_exp_f32_e32 v71, v32
	v_sub_f32_e32 v35, v181, v67
	v_exp_f32_e32 v32, v35
	v_pk_add_f32 v[34:35], v[36:37], v[38:39]
	v_pk_add_f32 v[64:65], v[40:41], v[42:43]
	v_pk_add_f32 v[72:73], v[68:69], v[70:71]
	v_pk_add_f32 v[34:35], v[34:35], v[64:65]
	v_pk_add_f32 v[64:65], v[44:45], v[46:47]
	v_pk_mul_f32 v[30:31], v[30:31], v[32:33] op_sel_hi:[1,0]
	v_pk_add_f32 v[64:65], v[64:65], v[72:73]
	v_pk_mul_f32 v[28:29], v[28:29], v[32:33] op_sel_hi:[1,0]
	v_pk_add_f32 v[34:35], v[34:35], v[64:65]
	v_pk_mul_f32 v[26:27], v[26:27], v[32:33] op_sel_hi:[1,0]
	v_add_f32_e32 v65, v34, v35
	v_pk_mul_f32 v[24:25], v[24:25], v[32:33] op_sel_hi:[1,0]
	v_pk_mul_f32 v[22:23], v[22:23], v[32:33] op_sel_hi:[1,0]
	v_pk_mul_f32 v[20:21], v[20:21], v[32:33] op_sel_hi:[1,0]
	v_pk_mul_f32 v[18:19], v[18:19], v[32:33] op_sel_hi:[1,0]
	v_pk_mul_f32 v[16:17], v[16:17], v[32:33] op_sel_hi:[1,0]
	v_pk_mul_f32 v[14:15], v[14:15], v[32:33] op_sel_hi:[1,0]
	v_pk_mul_f32 v[12:13], v[12:13], v[32:33] op_sel_hi:[1,0]
	v_pk_mul_f32 v[10:11], v[10:11], v[32:33] op_sel_hi:[1,0]
	v_pk_mul_f32 v[8:9], v[8:9], v[32:33] op_sel_hi:[1,0]
	v_pk_mul_f32 v[6:7], v[6:7], v[32:33] op_sel_hi:[1,0]
	v_pk_mul_f32 v[4:5], v[4:5], v[32:33] op_sel_hi:[1,0]
	v_pk_mul_f32 v[2:3], v[2:3], v[32:33] op_sel_hi:[1,0]
	v_pk_mul_f32 v[0:1], v[0:1], v[32:33] op_sel_hi:[1,0]
	v_fmac_f32_e32 v65, v175, v32
	v_cvt_pk_bf16_f32 v32, v36, v38
	v_cvt_pk_bf16_f32 v33, v40, v42
	v_cvt_pk_bf16_f32 v34, v44, v46
	v_cvt_pk_bf16_f32 v35, v68, v70
	v_cvt_pk_bf16_f32 v36, v37, v39
	v_cvt_pk_bf16_f32 v37, v41, v43
	v_cvt_pk_bf16_f32 v38, v45, v47
	v_cvt_pk_bf16_f32 v39, v69, v71
	s_waitcnt lgkmcnt(0)
	s_cmp_lt_i32 s8, s50
	s_nop 1
	v_mfma_f32_32x32x16_bf16 v[16:31], v[184:187], v[32:35], v[16:31]
	v_mfma_f32_32x32x16_bf16 v[16:31], v[188:191], v[36:39], v[16:31]
	v_mfma_f32_32x32x16_bf16 v[0:15], v[192:195], v[32:35], v[0:15]
	v_mfma_f32_32x32x16_bf16 v[0:15], v[196:199], v[36:39], v[0:15]
	s_cbranch_scc1 .LBB0_1253
	s_waitcnt vmcnt(15)
	v_mfma_f32_32x32x16_bf16 v[32:47], v[76:79], v[48:51], 0
	s_mov_b32 s0, 1
	s_waitcnt lgkmcnt(0)
	s_waitcnt vmcnt(11)
	ds_write_b128 v178, v[96:99]
	s_waitcnt vmcnt(10)
	ds_write_b128 v178, v[100:103] offset:512
	s_waitcnt vmcnt(9)
	ds_write_b128 v178, v[104:107] offset:1024
	s_waitcnt vmcnt(8)
	ds_write_b128 v178, v[108:111] offset:1536
	ds_read_b64_tr_b16 v[184:185], v179
	ds_read_b64_tr_b16 v[186:187], v179 offset:512
	ds_read_b64_tr_b16 v[188:189], v179 offset:1024
	ds_read_b64_tr_b16 v[190:191], v179 offset:1536
	ds_read_b64_tr_b16 v[192:193], v179 offset:2048
	ds_read_b64_tr_b16 v[194:195], v179 offset:2560
	ds_read_b64_tr_b16 v[196:197], v179 offset:3072
	ds_read_b64_tr_b16 v[198:199], v179 offset:3584
	v_lshl_add_u32 v64, s0, 5, v177
	v_sub_u32_e32 v66, v167, v64
	v_cvt_f32_i32_e32 v211, v66
	v_mfma_f32_32x32x16_bf16 v[32:47], v[80:83], v[52:55], v[32:47]
	v_lshlrev_b32_e32 v68, s30, v64
	v_cmp_gt_u32_e32 vcc, s6, v66
	v_cmp_lt_i32_e64 s[0:1], s3, v68
	v_or_b32_e32 v66, 1, v64
	s_and_b64 vcc, vcc, s[0:1]
	v_mfma_f32_32x32x16_bf16 v[32:47], v[84:87], v[56:59], v[32:47]
	v_mfma_f32_32x32x16_bf16 v[32:47], v[88:91], v[60:63], v[32:47]
	s_nop 11
	v_sub_u32_e32 v211, v167, v64
	v_add_u32_e32 v170, 0xffffffe5, v211
	v_cmp_le_u32_e32 vcc, 0x66, v170
	v_lshlrev_b32_e32 v170, s30, v64
	s_nop 2
	s_cbranch_vccnz .Ldil_slow_3
	v_cmp_ge_i32_e32 vcc, s3, v170
	s_nop 3
	s_cbranch_vccnz .Ldil_slow_3
	v_cvt_f32_i32_e32 v170, v211
	v_mul_f32_e32 v170, v171, v170
	v_fma_f32 v32, v32, v210, -v170
	v_fma_f32 v33, v33, v210, -v170
	v_fmamk_f32 v33, v171, 0x3f800000, v33
	v_fma_f32 v68, v34, v210, -v170
	v_fmamk_f32 v68, v171, 0x40000000, v68
	v_fma_f32 v69, v35, v210, -v170
	v_fmamk_f32 v69, v171, 0x40400000, v69
	v_fma_f32 v70, v36, v210, -v170
	v_fmamk_f32 v70, v171, 0x41000000, v70
	v_fma_f32 v37, v37, v210, -v170
	v_fmamk_f32 v37, v171, 0x41100000, v37
	v_fma_f32 v71, v38, v210, -v170
	v_fmamk_f32 v71, v171, 0x41200000, v71
	v_fma_f32 v39, v39, v210, -v170
	v_fmamk_f32 v39, v171, 0x41300000, v39
	v_fma_f32 v72, v40, v210, -v170
	v_fmamk_f32 v72, v171, 0x41800000, v72
	v_fma_f32 v41, v41, v210, -v170
	v_fmamk_f32 v41, v171, 0x41880000, v41
	v_fma_f32 v73, v42, v210, -v170
	v_fmamk_f32 v73, v171, 0x41900000, v73
	v_fma_f32 v43, v43, v210, -v170
	v_fmamk_f32 v43, v171, 0x41980000, v43
	v_fma_f32 v74, v44, v210, -v170
	v_fmamk_f32 v74, v171, 0x41c00000, v74
	v_fma_f32 v75, v45, v210, -v170
	v_fmamk_f32 v75, v171, 0x41c80000, v75
	v_fma_f32 v76, v46, v210, -v170
	v_fmamk_f32 v76, v171, 0x41d00000, v76
	v_fma_f32 v34, v47, v210, -v170
	v_fmamk_f32 v34, v171, 0x41d80000, v34
	s_branch .Ldil_join_3

.Ldil_join_3:
	v_max_f32_e32 v42, v76, v34
	v_max_f32_e32 v35, v68, v69
	v_max_f32_e32 v36, v71, v39
	v_max_f32_e32 v38, v72, v41
	v_max_f32_e32 v40, v73, v43
	v_max3_f32 v42, v74, v75, v42
	v_max3_f32 v35, v32, v33, v35
	v_max3_f32 v36, v70, v37, v36
	v_max3_f32 v38, v38, v40, v42
	v_max3_f32 v35, v35, v36, v38
	v_mov_b32_e32 v36, v35
	s_nop 1
	v_permlane32_swap_b32_e32 v35, v36
	v_max3_f32 v66, v67, v35, v36
	v_sub_f32_e32 v32, v32, v66
	v_exp_f32_e32 v36, v32
	v_sub_f32_e32 v32, v33, v66
	v_exp_f32_e32 v38, v32
	v_sub_f32_e32 v32, v68, v66
	v_exp_f32_e32 v40, v32
	v_sub_f32_e32 v32, v69, v66
	v_exp_f32_e32 v42, v32
	v_sub_f32_e32 v32, v70, v66
	v_exp_f32_e32 v44, v32
	v_sub_f32_e32 v32, v37, v66
	v_exp_f32_e32 v46, v32
	v_sub_f32_e32 v32, v71, v66
	v_exp_f32_e32 v68, v32
	v_sub_f32_e32 v32, v39, v66
	v_exp_f32_e32 v70, v32
	v_sub_f32_e32 v32, v72, v66
	v_exp_f32_e32 v37, v32
	v_sub_f32_e32 v32, v41, v66
	v_exp_f32_e32 v39, v32
	v_sub_f32_e32 v32, v73, v66
	v_exp_f32_e32 v41, v32
	v_sub_f32_e32 v32, v43, v66
	v_exp_f32_e32 v43, v32
	v_sub_f32_e32 v32, v74, v66
	v_exp_f32_e32 v45, v32
	v_sub_f32_e32 v32, v75, v66
	v_exp_f32_e32 v47, v32
	v_sub_f32_e32 v32, v76, v66
	v_exp_f32_e32 v69, v32
	v_sub_f32_e32 v32, v34, v66
	v_exp_f32_e32 v71, v32
	v_sub_f32_e32 v35, v67, v66
	v_exp_f32_e32 v32, v35
	v_pk_add_f32 v[34:35], v[36:37], v[38:39]
	v_pk_add_f32 v[72:73], v[40:41], v[42:43]
	v_pk_add_f32 v[74:75], v[68:69], v[70:71]
	v_pk_add_f32 v[34:35], v[34:35], v[72:73]
	v_pk_add_f32 v[72:73], v[44:45], v[46:47]
	v_pk_mul_f32 v[30:31], v[30:31], v[32:33] op_sel_hi:[1,0]
	v_pk_add_f32 v[72:73], v[72:73], v[74:75]
	v_pk_mul_f32 v[28:29], v[28:29], v[32:33] op_sel_hi:[1,0]
	v_pk_add_f32 v[34:35], v[34:35], v[72:73]
	v_pk_mul_f32 v[26:27], v[26:27], v[32:33] op_sel_hi:[1,0]
	v_add_f32_e32 v64, v34, v35
	v_pk_mul_f32 v[24:25], v[24:25], v[32:33] op_sel_hi:[1,0]
	v_pk_mul_f32 v[22:23], v[22:23], v[32:33] op_sel_hi:[1,0]
	v_pk_mul_f32 v[20:21], v[20:21], v[32:33] op_sel_hi:[1,0]
	v_pk_mul_f32 v[18:19], v[18:19], v[32:33] op_sel_hi:[1,0]
	v_pk_mul_f32 v[16:17], v[16:17], v[32:33] op_sel_hi:[1,0]
	v_pk_mul_f32 v[14:15], v[14:15], v[32:33] op_sel_hi:[1,0]
	v_pk_mul_f32 v[12:13], v[12:13], v[32:33] op_sel_hi:[1,0]
	v_pk_mul_f32 v[10:11], v[10:11], v[32:33] op_sel_hi:[1,0]
	v_pk_mul_f32 v[8:9], v[8:9], v[32:33] op_sel_hi:[1,0]
	v_pk_mul_f32 v[6:7], v[6:7], v[32:33] op_sel_hi:[1,0]
	v_pk_mul_f32 v[4:5], v[4:5], v[32:33] op_sel_hi:[1,0]
	v_pk_mul_f32 v[2:3], v[2:3], v[32:33] op_sel_hi:[1,0]
	v_pk_mul_f32 v[0:1], v[0:1], v[32:33] op_sel_hi:[1,0]
	v_fmac_f32_e32 v64, v65, v32
	v_cvt_pk_bf16_f32 v32, v36, v38
	v_cvt_pk_bf16_f32 v33, v40, v42
	v_cvt_pk_bf16_f32 v34, v44, v46
	v_cvt_pk_bf16_f32 v35, v68, v70
	v_cvt_pk_bf16_f32 v36, v37, v39
	v_cvt_pk_bf16_f32 v37, v41, v43
	v_cvt_pk_bf16_f32 v38, v45, v47
	v_cvt_pk_bf16_f32 v39, v69, v71
	s_waitcnt lgkmcnt(0)
	s_cmp_lt_i32 s8, s51
	s_nop 1
	v_mfma_f32_32x32x16_bf16 v[16:31], v[184:187], v[32:35], v[16:31]
	v_mfma_f32_32x32x16_bf16 v[16:31], v[188:191], v[36:39], v[16:31]
	v_mfma_f32_32x32x16_bf16 v[0:15], v[192:195], v[32:35], v[0:15]
	v_mfma_f32_32x32x16_bf16 v[0:15], v[196:199], v[36:39], v[0:15]
	s_cbranch_scc1 .LBB0_1252
	s_waitcnt vmcnt(7)
	v_mfma_f32_32x32x16_bf16 v[32:47], v[124:127], v[48:51], 0
	s_mov_b32 s0, s19
	s_waitcnt lgkmcnt(0)
	s_waitcnt vmcnt(3)
	ds_write_b128 v178, v[144:147]
	s_waitcnt vmcnt(2)
	ds_write_b128 v178, v[148:151] offset:512
	s_waitcnt vmcnt(1)
	ds_write_b128 v178, v[152:155] offset:1024
	s_waitcnt vmcnt(0)
	ds_write_b128 v178, v[156:159] offset:1536
	ds_read_b64_tr_b16 v[184:185], v179
	ds_read_b64_tr_b16 v[186:187], v179 offset:512
	ds_read_b64_tr_b16 v[188:189], v179 offset:1024
	ds_read_b64_tr_b16 v[190:191], v179 offset:1536
	ds_read_b64_tr_b16 v[192:193], v179 offset:2048
	ds_read_b64_tr_b16 v[194:195], v179 offset:2560
	ds_read_b64_tr_b16 v[196:197], v179 offset:3072
	ds_read_b64_tr_b16 v[198:199], v179 offset:3584
	v_lshl_add_u32 v48, s0, 5, v177
	v_sub_u32_e32 v49, v167, v48
	v_cvt_f32_i32_e32 v211, v49
	v_mfma_f32_32x32x16_bf16 v[32:47], v[128:131], v[52:55], v[32:47]
	v_lshlrev_b32_e32 v50, s30, v48
	v_cmp_gt_u32_e32 vcc, s6, v49
	v_cmp_lt_i32_e64 s[0:1], s3, v50
	v_or_b32_e32 v49, 1, v48
	s_and_b64 vcc, vcc, s[0:1]
	v_mfma_f32_32x32x16_bf16 v[32:47], v[132:135], v[56:59], v[32:47]
	v_mfma_f32_32x32x16_bf16 v[32:47], v[136:139], v[60:63], v[32:47]
	s_nop 11
	v_sub_u32_e32 v211, v167, v48
	v_cmp_gt_i32_e32 vcc, 27, v211
	v_lshlrev_b32_e32 v170, s30, v48
	s_nop 2
	s_cbranch_vccnz .Ldil_slow_4
	v_cmp_ge_i32_e32 vcc, s3, v170
	s_nop 3
	s_cbranch_vccnz .Ldil_slow_4
	v_cvt_f32_i32_e32 v170, v211
	v_mul_f32_e32 v170, v171, v170
	v_add_u32_e32 v211, 0xffffff80, v211
	v_fma_f32 v32, v32, v210, -v170
	v_cmp_ge_i32_e32 vcc, 0, v211
	v_fma_f32 v33, v33, v210, -v170
	v_fmamk_f32 v33, v171, 0x3f800000, v33
	v_cndmask_b32_e32 v32, v243, v32, vcc
	v_cmp_ge_i32_e32 vcc, 1, v211
	v_fma_f32 v49, v34, v210, -v170
	v_fmamk_f32 v49, v171, 0x40000000, v49
	v_cndmask_b32_e32 v33, v243, v33, vcc
	v_cmp_ge_i32_e32 vcc, 2, v211
	v_fma_f32 v50, v35, v210, -v170
	v_fmamk_f32 v50, v171, 0x40400000, v50
	v_cndmask_b32_e32 v49, v243, v49, vcc
	v_cmp_ge_i32_e32 vcc, 3, v211
	v_fma_f32 v51, v36, v210, -v170
	v_fmamk_f32 v51, v171, 0x41000000, v51
	v_cndmask_b32_e32 v50, v243, v50, vcc
	v_cmp_ge_i32_e32 vcc, 8, v211
	v_fma_f32 v37, v37, v210, -v170
	v_fmamk_f32 v37, v171, 0x41100000, v37
	v_cndmask_b32_e32 v51, v243, v51, vcc
	v_cmp_ge_i32_e32 vcc, 9, v211
	v_fma_f32 v52, v38, v210, -v170
	v_fmamk_f32 v52, v171, 0x41200000, v52
	v_cndmask_b32_e32 v37, v243, v37, vcc
	v_cmp_ge_i32_e32 vcc, 10, v211
	v_fma_f32 v39, v39, v210, -v170
	v_fmamk_f32 v39, v171, 0x41300000, v39
	v_cndmask_b32_e32 v52, v243, v52, vcc
	v_cmp_ge_i32_e32 vcc, 11, v211
	v_fma_f32 v53, v40, v210, -v170
	v_fmamk_f32 v53, v171, 0x41800000, v53
	v_cndmask_b32_e32 v39, v243, v39, vcc
	v_cmp_ge_i32_e32 vcc, 16, v211
	v_fma_f32 v41, v41, v210, -v170
	v_fmamk_f32 v41, v171, 0x41880000, v41
	v_cndmask_b32_e32 v53, v243, v53, vcc
	v_cmp_ge_i32_e32 vcc, 17, v211
	v_fma_f32 v42, v42, v210, -v170
	v_fmamk_f32 v42, v171, 0x41900000, v42
	v_cndmask_b32_e32 v41, v243, v41, vcc
	v_cmp_ge_i32_e32 vcc, 18, v211
	v_fma_f32 v43, v43, v210, -v170
	v_fmamk_f32 v43, v171, 0x41980000, v43
	v_cndmask_b32_e32 v42, v243, v42, vcc
	v_cmp_ge_i32_e32 vcc, 19, v211
	v_fma_f32 v44, v44, v210, -v170
	v_fmamk_f32 v44, v171, 0x41c00000, v44
	v_cndmask_b32_e32 v43, v243, v43, vcc
	v_cmp_ge_i32_e32 vcc, 24, v211
	v_fma_f32 v45, v45, v210, -v170
	v_fmamk_f32 v45, v171, 0x41c80000, v45
	v_cndmask_b32_e32 v44, v243, v44, vcc
	v_cmp_ge_i32_e32 vcc, 25, v211
	v_fma_f32 v54, v46, v210, -v170
	v_fmamk_f32 v54, v171, 0x41d00000, v54
	v_cndmask_b32_e32 v45, v243, v45, vcc
	v_cmp_ge_i32_e32 vcc, 26, v211
	v_fma_f32 v55, v47, v210, -v170
	v_fmamk_f32 v55, v171, 0x41d80000, v55
	v_cndmask_b32_e32 v54, v243, v54, vcc
	v_cmp_ge_i32_e32 vcc, 27, v211
	s_nop 1
	v_cndmask_b32_e32 v55, v243, v55, vcc
	s_branch .Ldil_join_4

.Ldil_join_4:
	v_max_f32_e32 v40, v54, v55
	v_max_f32_e32 v34, v49, v50
	v_max_f32_e32 v35, v52, v39
	v_max_f32_e32 v36, v53, v41
	v_max_f32_e32 v38, v42, v43
	v_max3_f32 v40, v44, v45, v40
	v_max3_f32 v34, v32, v33, v34
	v_max3_f32 v35, v51, v37, v35
	v_max3_f32 v36, v36, v38, v40
	v_max3_f32 v34, v34, v35, v36
	v_mov_b32_e32 v35, v34
	s_nop 1
	v_permlane32_swap_b32_e32 v34, v35
	v_max3_f32 v56, v66, v34, v35
	v_sub_f32_e32 v33, v33, v56
	v_exp_f32_e32 v34, v33
	v_sub_f32_e32 v33, v49, v56
	v_exp_f32_e32 v36, v33
	v_sub_f32_e32 v33, v50, v56
	v_exp_f32_e32 v38, v33
	v_sub_f32_e32 v33, v51, v56
	v_exp_f32_e32 v40, v33
	v_sub_f32_e32 v33, v37, v56
	v_exp_f32_e32 v46, v33
	v_sub_f32_e32 v33, v52, v56
	v_exp_f32_e32 v48, v33
	v_sub_f32_e32 v33, v39, v56
	v_sub_f32_e32 v37, v42, v56
	v_sub_f32_e32 v42, v45, v56
	v_sub_f32_e32 v32, v32, v56
	v_exp_f32_e32 v50, v33
	v_sub_f32_e32 v33, v53, v56
	v_sub_f32_e32 v35, v41, v56
	v_sub_f32_e32 v39, v43, v56
	v_exp_f32_e32 v47, v42
	v_sub_f32_e32 v42, v54, v56
	v_exp_f32_e32 v32, v32
	v_exp_f32_e32 v33, v33
	v_exp_f32_e32 v35, v35
	v_exp_f32_e32 v37, v37
	v_exp_f32_e32 v39, v39
	v_sub_f32_e32 v41, v44, v56
	v_exp_f32_e32 v49, v42
	v_sub_f32_e32 v42, v55, v56
	v_exp_f32_e32 v41, v41
	v_exp_f32_e32 v51, v42
	v_sub_f32_e32 v57, v66, v56
	v_pk_add_f32 v[44:45], v[32:33], v[34:35]
	v_pk_add_f32 v[52:53], v[36:37], v[38:39]
	v_exp_f32_e32 v42, v57
	v_pk_add_f32 v[44:45], v[44:45], v[52:53]
	v_pk_add_f32 v[52:53], v[40:41], v[46:47]
	v_pk_add_f32 v[54:55], v[48:49], v[50:51]
	v_pk_mul_f32 v[30:31], v[30:31], v[42:43] op_sel_hi:[1,0]
	v_pk_add_f32 v[52:53], v[52:53], v[54:55]
	v_pk_mul_f32 v[28:29], v[28:29], v[42:43] op_sel_hi:[1,0]
	v_pk_add_f32 v[44:45], v[44:45], v[52:53]
	v_pk_mul_f32 v[26:27], v[26:27], v[42:43] op_sel_hi:[1,0]
	v_add_f32_e32 v52, v44, v45
	v_pk_mul_f32 v[24:25], v[24:25], v[42:43] op_sel_hi:[1,0]
	v_pk_mul_f32 v[22:23], v[22:23], v[42:43] op_sel_hi:[1,0]
	v_pk_mul_f32 v[20:21], v[20:21], v[42:43] op_sel_hi:[1,0]
	v_pk_mul_f32 v[18:19], v[18:19], v[42:43] op_sel_hi:[1,0]
	v_pk_mul_f32 v[16:17], v[16:17], v[42:43] op_sel_hi:[1,0]
	v_pk_mul_f32 v[14:15], v[14:15], v[42:43] op_sel_hi:[1,0]
	v_pk_mul_f32 v[12:13], v[12:13], v[42:43] op_sel_hi:[1,0]
	v_pk_mul_f32 v[10:11], v[10:11], v[42:43] op_sel_hi:[1,0]
	v_pk_mul_f32 v[8:9], v[8:9], v[42:43] op_sel_hi:[1,0]
	v_pk_mul_f32 v[6:7], v[6:7], v[42:43] op_sel_hi:[1,0]
	v_pk_mul_f32 v[4:5], v[4:5], v[42:43] op_sel_hi:[1,0]
	v_pk_mul_f32 v[2:3], v[2:3], v[42:43] op_sel_hi:[1,0]
	v_pk_mul_f32 v[0:1], v[0:1], v[42:43] op_sel_hi:[1,0]
	v_fmac_f32_e32 v52, v64, v42
	v_cvt_pk_bf16_f32 v42, v32, v34
	v_cvt_pk_bf16_f32 v43, v36, v38
	v_cvt_pk_bf16_f32 v44, v40, v46
	v_cvt_pk_bf16_f32 v45, v48, v50
	v_cvt_pk_bf16_f32 v32, v33, v35
	v_cvt_pk_bf16_f32 v33, v37, v39
	v_cvt_pk_bf16_f32 v34, v41, v47
	v_cvt_pk_bf16_f32 v35, v49, v51
	s_waitcnt lgkmcnt(0)
	v_mov_b32_e32 v66, v56
	v_mov_b32_e32 v64, v52
	s_nop 1
	v_mfma_f32_32x32x16_bf16 v[16:31], v[184:187], v[42:45], v[16:31]
	v_mfma_f32_32x32x16_bf16 v[16:31], v[188:191], v[32:35], v[16:31]
	v_mfma_f32_32x32x16_bf16 v[0:15], v[192:195], v[42:45], v[0:15]
	v_mfma_f32_32x32x16_bf16 v[0:15], v[196:199], v[32:35], v[0:15]
